# attention online softmax: O/l rescale skipped unless the running row max grows by more than 8 (log2 units) for some query of the wave; stale max kept otherwise (exact softmax, alpha=1)
# speedup vs baseline: 1.0110x; 1.0090x over previous
.LBB0_720:
	s_or_b64 exec, exec, s[10:11]
	s_and_b32 s13, 1, s12
	s_cselect_b32 s10, 0, 0x8c00
	s_add_i32 s10, s10, 16
	v_add3_u32 v114, s10, v158, v105
	ds_read_b128 v[118:121], v114
	ds_read_b128 v[122:125], v114 offset:64
	ds_read_b128 v[126:129], v114 offset:4352
	ds_read_b128 v[130:133], v114 offset:4416
	s_waitcnt lgkmcnt(3)
	v_mfma_f32_16x16x32_bf16 v[118:121], v[118:121], v[36:39], 0
	s_waitcnt lgkmcnt(1)
	v_mfma_f32_16x16x32_bf16 v[126:129], v[126:129], v[36:39], 0
	s_nop 0
	v_mfma_f32_16x16x32_bf16 v[118:121], v[122:125], v[40:43], v[118:121]
	ds_read_b128 v[122:125], v114 offset:8704
	s_waitcnt lgkmcnt(1)
	v_mfma_f32_16x16x32_bf16 v[126:129], v[130:133], v[40:43], v[126:129]
	ds_read_b128 v[130:133], v114 offset:8768
	ds_read_b128 v[138:141], v114 offset:13056
	ds_read_b128 v[160:163], v114 offset:13120
	s_waitcnt lgkmcnt(3)
	v_mfma_f32_16x16x32_bf16 v[122:125], v[122:125], v[36:39], 0
	s_waitcnt lgkmcnt(2)
	v_mfma_f32_16x16x32_bf16 v[130:133], v[130:133], v[40:43], v[122:125]
	s_nop 5
	v_max3_f32 v122, v118, s26, v119
	v_max3_f32 v122, v122, v120, v121
	v_max3_f32 v134, v122, v126, v127
	s_waitcnt lgkmcnt(1)
	v_mfma_f32_16x16x32_bf16 v[122:125], v[138:141], v[36:39], 0
	v_max3_f32 v134, v134, v128, v129
	v_max3_f32 v134, v134, v130, v131
	v_max3_f32 v134, v134, v132, v133
	s_waitcnt lgkmcnt(0)
	v_mfma_f32_16x16x32_bf16 v[138:141], v[160:163], v[40:43], v[122:125]
	s_nop 7
	v_max3_f32 v122, v134, v138, v139
	v_max3_f32 v122, v122, v140, v141
	v_mul_f32_e32 v134, 0x3e38aa3b, v122
	v_mul_f32_e32 v135, 0x3e38aa3b, v122
	ds_read_b128 v[122:125], v114 offset:128
	ds_read_b128 v[166:169], v114 offset:192
	ds_read_b128 v[170:173], v114 offset:4544
	s_nop 0
	v_permlane16_swap_b32_e32 v134, v135
	v_max_f32_e32 v134, v134, v135
	v_mov_b32_e32 v135, v134
	s_nop 1
	v_permlane32_swap_b32_e32 v134, v135
	s_waitcnt lgkmcnt(2)
	v_mfma_f32_16x16x32_bf16 v[122:125], v[122:125], v[48:51], 0
	v_max3_f32 v159, v117, v134, v135
	v_sub_f32_e32 v134, v117, v159
	v_cmp_gt_f32_e32 vcc, 0xc1000000, v134
	s_cmp_lg_u64 vcc, 0
	s_cselect_b32 s98, 1, 0
	s_cbranch_scc1 .Lmy_at_k0
	v_mov_b32_e32 v159, v117
	v_mov_b32_e32 v134, 0
.Lmy_at_k0:
	v_fma_f32 v117, v118, s27, -v159
	v_fma_f32 v118, v119, s27, -v159
	v_fma_f32 v119, v120, s27, -v159
	v_fma_f32 v120, v121, s27, -v159
	v_exp_f32_e32 v162, v118
	v_exp_f32_e32 v163, v119
	v_exp_f32_e32 v164, v120
	ds_read_b128 v[118:121], v114 offset:4480
	s_waitcnt lgkmcnt(2)
	v_mfma_f32_16x16x32_bf16 v[174:177], v[166:169], v[52:55], v[122:125]
	v_exp_f32_e32 v161, v117
	v_fma_f32 v117, v126, s27, -v159
	v_exp_f32_e32 v165, v117
	ds_read_b128 v[122:125], v114 offset:8832
	s_waitcnt lgkmcnt(1)
	v_mfma_f32_16x16x32_bf16 v[118:121], v[118:121], v[48:51], 0
	v_fma_f32 v117, v127, s27, -v159
	v_exp_f32_e32 v166, v117
	v_fma_f32 v117, v128, s27, -v159
	v_fma_f32 v135, v129, s27, -v159
	ds_read_b128 v[126:129], v114 offset:8896
	v_mfma_f32_16x16x32_bf16 v[178:181], v[170:173], v[52:55], v[118:121]
	ds_read_b128 v[168:171], v114 offset:13184
	ds_read_b128 v[182:185], v114 offset:13248
	v_fma_f32 v114, v132, s27, -v159
	s_waitcnt lgkmcnt(3)
	v_mfma_f32_16x16x32_bf16 v[122:125], v[122:125], v[48:51], 0
	v_fma_f32 v118, v130, s27, -v159
	v_exp_f32_e32 v121, v118
	v_fma_f32 v118, v131, s27, -v159
	s_waitcnt lgkmcnt(2)
	v_mfma_f32_16x16x32_bf16 v[186:189], v[126:129], v[52:55], v[122:125]
	v_exp_f32_e32 v119, v135
	v_exp_f32_e32 v136, v134
	v_exp_f32_e32 v117, v117
	s_cmp_eq_u32 s98, 0
	s_cbranch_scc1 .Lmy_at_s0
	v_pk_mul_f32 v[98:99], v[98:99], v[136:137] op_sel_hi:[1,0]
	v_pk_mul_f32 v[96:97], v[96:97], v[136:137] op_sel_hi:[1,0]
	v_pk_mul_f32 v[94:95], v[94:95], v[136:137] op_sel_hi:[1,0]
	v_pk_mul_f32 v[92:93], v[92:93], v[136:137] op_sel_hi:[1,0]
	v_mul_f32_e64 v78, v78, v136
	v_mul_f32_e64 v79, v79, v136
	v_pk_mul_f32 v[76:77], v[76:77], v[136:137] op_sel_hi:[1,0]
	v_pk_mul_f32 v[74:75], v[74:75], v[136:137] op_sel_hi:[1,0]
	v_pk_mul_f32 v[72:73], v[72:73], v[136:137] op_sel_hi:[1,0]
	v_mul_f32_e64 v62, v62, v136
	v_mul_f32_e64 v63, v63, v136
	v_pk_mul_f32 v[60:61], v[60:61], v[136:137] op_sel_hi:[1,0]
	v_pk_mul_f32 v[30:31], v[30:31], v[136:137] op_sel_hi:[1,0]
	v_mul_f32_e64 v28, v28, v136
	v_mul_f32_e64 v29, v29, v136
	v_pk_mul_f32 v[22:23], v[22:23], v[136:137] op_sel_hi:[1,0]
	v_pk_mul_f32 v[20:21], v[20:21], v[136:137] op_sel_hi:[1,0]
	v_pk_mul_f32 v[86:87], v[86:87], v[136:137] op_sel_hi:[1,0]
	v_pk_mul_f32 v[84:85], v[84:85], v[136:137] op_sel_hi:[1,0]
.Lmy_at_s0:
	s_waitcnt lgkmcnt(1)
	v_mfma_f32_16x16x32_bf16 v[128:131], v[168:171], v[48:51], 0
	v_exp_f32_e32 v123, v118
	v_max3_f32 v118, v174, s26, v175
	v_max3_f32 v118, v118, v176, v177
	s_waitcnt lgkmcnt(0)
	v_mfma_f32_16x16x32_bf16 v[182:185], v[182:185], v[52:55], v[128:131]
	v_max3_f32 v118, v118, v178, v179
	v_max3_f32 v118, v118, v180, v181
	v_max3_f32 v118, v118, v186, v187
	v_max3_f32 v118, v118, v188, v189
	v_exp_f32_e32 v125, v114
	s_nop 2
	v_max3_f32 v118, v118, v182, v183
	v_max3_f32 v118, v118, v184, v185
	v_mul_f32_e32 v118, 0x3e38aa3b, v118
	v_fma_f32 v114, v133, s27, -v159
	v_mov_b32_e32 v120, v118
	v_exp_f32_e32 v127, v114
	v_fma_f32 v114, v138, s27, -v159
	v_permlane16_swap_b32_e32 v118, v120
	v_exp_f32_e32 v129, v114
	v_max_f32_e32 v118, v118, v120
	v_fma_f32 v114, v139, s27, -v159
	v_mov_b32_e32 v120, v118
	v_exp_f32_e32 v131, v114
	v_fma_f32 v114, v140, s27, -v159
	v_permlane32_swap_b32_e32 v118, v120
	v_exp_f32_e32 v133, v114
	v_fma_f32 v114, v141, s27, -v159
	v_max3_f32 v160, v116, v118, v120
	v_exp_f32_e32 v135, v114
	v_sub_f32_e32 v114, v116, v160
	v_cmp_gt_f32_e32 vcc, 0xc1000000, v114
	s_cmp_lg_u64 vcc, 0
	s_cselect_b32 s99, 1, 0
	s_cbranch_scc1 .Lmy_at_k1
	v_mov_b32_e32 v160, v116
	v_mov_b32_e32 v114, 0
.Lmy_at_k1:
	v_fma_f32 v116, v174, s27, -v160
	v_exp_f32_e32 v167, v116
	v_fma_f32 v116, v175, s27, -v160
	v_exp_f32_e32 v168, v116
	v_fma_f32 v116, v176, s27, -v160
	v_exp_f32_e32 v169, v116
	v_fma_f32 v116, v177, s27, -v160
	v_exp_f32_e32 v138, v114
	v_lshlrev_b32_e32 v114, 1, v3
	s_cmp_eq_u32 s99, 0
	s_cbranch_scc1 .Lmy_at_s1
	v_pk_mul_f32 v[82:83], v[82:83], v[138:139] op_sel_hi:[1,0]
	v_pk_mul_f32 v[80:81], v[80:81], v[138:139] op_sel_hi:[1,0]
	v_pk_mul_f32 v[70:71], v[70:71], v[138:139] op_sel_hi:[1,0]
	v_pk_mul_f32 v[68:69], v[68:69], v[138:139] op_sel_hi:[1,0]
	v_mul_f32_e64 v58, v58, v138
	v_mul_f32_e64 v59, v59, v138
	v_pk_mul_f32 v[56:57], v[56:57], v[138:139] op_sel_hi:[1,0]
	v_pk_mul_f32 v[26:27], v[26:27], v[138:139] op_sel_hi:[1,0]
	v_pk_mul_f32 v[24:25], v[24:25], v[138:139] op_sel_hi:[1,0]
	v_pk_mul_f32 v[66:67], v[66:67], v[138:139] op_sel_hi:[1,0]
	v_pk_mul_f32 v[64:65], v[64:65], v[138:139] op_sel_hi:[1,0]
	v_pk_mul_f32 v[46:47], v[46:47], v[138:139] op_sel_hi:[1,0]
	v_pk_mul_f32 v[44:45], v[44:45], v[138:139] op_sel_hi:[1,0]
	v_mul_f32_e64 v34, v34, v138
	v_mul_f32_e64 v35, v35, v138
	v_pk_mul_f32 v[32:33], v[32:33], v[138:139] op_sel_hi:[1,0]
	v_pk_mul_f32 v[90:91], v[90:91], v[138:139] op_sel_hi:[1,0]
	v_pk_mul_f32 v[88:89], v[88:89], v[138:139] op_sel_hi:[1,0]
.Lmy_at_s1:
	v_exp_f32_e32 v170, v116
	v_fma_f32 v116, v178, s27, -v160
	v_add3_u32 v139, s10, v115, v114
	v_add3_u32 v178, s10, v152, v114
	v_add_u32_e32 v173, 0x4000, v139
	v_add_u32_e32 v190, 0x4000, v178
	v_fma_f32 v128, v182, s27, -v160
	v_fma_f32 v130, v183, s27, -v160
	v_fma_f32 v132, v184, s27, -v160
	v_fma_f32 v134, v185, s27, -v160
	ds_read_b64 v[174:175], v173 offset:1024
	ds_read_b64 v[176:177], v173 offset:1056
	ds_read_b64 v[182:183], v190 offset:1024
	ds_read_b64 v[184:185], v190 offset:1056
	v_exp_f32_e32 v171, v116
	v_fma_f32 v116, v179, s27, -v160
	v_exp_f32_e32 v172, v116
	v_fma_f32 v116, v180, s27, -v160
	v_fma_f32 v118, v181, s27, -v160
	v_exp_f32_e32 v116, v116
	v_exp_f32_e32 v118, v118
	v_cvt_pk_bf16_f32 v143, v117, v119
	v_cvt_pk_bf16_f32 v142, v165, v166
	v_cvt_pk_bf16_f32 v141, v163, v164
	v_cvt_pk_bf16_f32 v140, v161, v162
	v_cvt_pk_bf16_f32 v181, v116, v118
	v_cvt_pk_bf16_f32 v180, v171, v172
	v_cvt_pk_bf16_f32 v179, v169, v170
	v_cvt_pk_bf16_f32 v178, v167, v168
	s_waitcnt lgkmcnt(2)
	v_mfma_f32_16x16x32_bf16 v[96:99], v[174:177], v[140:143], v[96:99]
	v_mfma_f32_16x16x32_bf16 v[80:83], v[174:177], v[178:181], v[80:83]
	v_add3_u32 v174, s10, v153, v114
	v_add_u32_e32 v191, 0x4000, v174
	ds_read_b64 v[174:175], v191 offset:1024
	ds_read_b64 v[176:177], v191 offset:1056
	s_waitcnt lgkmcnt(2)
	v_mfma_f32_16x16x32_bf16 v[92:95], v[182:185], v[140:143], v[92:95]
	v_mfma_f32_16x16x32_bf16 v[68:71], v[182:185], v[178:181], v[68:71]
	v_add3_u32 v182, s10, v154, v114
	v_add_u32_e32 v192, 0x4000, v182
	ds_read_b64 v[182:183], v192 offset:1024
	ds_read_b64 v[184:185], v192 offset:1056
	v_add_u32_e32 v193, 0x6800, v139
	v_add_u32_e32 v194, 0x7000, v139
	s_waitcnt lgkmcnt(2)
	v_mfma_f32_16x16x32_bf16 v[76:79], v[174:177], v[140:143], v[76:79]
	v_mfma_f32_16x16x32_bf16 v[56:59], v[174:177], v[178:181], v[56:59]
	ds_read_b64 v[174:175], v193
	ds_read_b64 v[176:177], v193 offset:32
	s_waitcnt lgkmcnt(2)
	v_mfma_f32_16x16x32_bf16 v[72:75], v[182:185], v[140:143], v[72:75]
	v_add_u32_e32 v195, 0x7800, v139
	v_mfma_f32_16x16x32_bf16 v[24:27], v[182:185], v[178:181], v[24:27]
	ds_read_b64 v[182:183], v194 offset:256
	ds_read_b64 v[184:185], v194 offset:288
	v_add_u32_e32 v139, 0x8000, v139
	s_waitcnt lgkmcnt(2)
	v_mfma_f32_16x16x32_bf16 v[60:63], v[174:177], v[140:143], v[60:63]
	v_mfma_f32_16x16x32_bf16 v[64:67], v[174:177], v[178:181], v[64:67]
	ds_read_b64 v[174:175], v195 offset:512
	ds_read_b64 v[176:177], v195 offset:544
	v_fma_f32 v120, v186, s27, -v160
	s_waitcnt lgkmcnt(2)
	v_mfma_f32_16x16x32_bf16 v[28:31], v[182:185], v[140:143], v[28:31]
	v_fma_f32 v122, v187, s27, -v160
	v_fma_f32 v124, v188, s27, -v160
	v_fma_f32 v126, v189, s27, -v160
	v_mfma_f32_16x16x32_bf16 v[44:47], v[182:185], v[178:181], v[44:47]
	ds_read_b64 v[182:183], v139 offset:768
	ds_read_b64 v[184:185], v139 offset:800
	ds_read_b64 v[196:197], v190 offset:1088
	ds_read_b64 v[198:199], v190 offset:1120
	ds_read_b64 v[200:201], v173 offset:1088
	ds_read_b64 v[202:203], v173 offset:1120
	ds_read_b64 v[204:205], v191 offset:1088
	ds_read_b64 v[206:207], v191 offset:1120
	ds_read_b64 v[208:209], v192 offset:1088
	ds_read_b64 v[210:211], v192 offset:1120
	ds_read_b64 v[212:213], v193 offset:64
	ds_read_b64 v[214:215], v193 offset:96
	ds_read_b64 v[216:217], v194 offset:320
	ds_read_b64 v[218:219], v194 offset:352
	ds_read_b64 v[220:221], v195 offset:576
	ds_read_b64 v[222:223], v195 offset:608
	ds_read_b64 v[226:227], v139 offset:832
	ds_read_b64 v[228:229], v139 offset:864
	v_exp_f32_e32 v120, v120
	v_exp_f32_e32 v122, v122
	s_waitcnt lgkmcnt(15)
	v_mfma_f32_16x16x32_bf16 v[32:35], v[174:177], v[178:181], v[32:35]
	v_exp_f32_e32 v124, v124
	v_exp_f32_e32 v126, v126
	v_exp_f32_e32 v128, v128
	s_waitcnt lgkmcnt(15)
	v_mfma_f32_16x16x32_bf16 v[88:91], v[182:185], v[178:181], v[88:91]
	v_exp_f32_e32 v130, v130
	v_exp_f32_e32 v132, v132
	v_exp_f32_e32 v134, v134
	v_mfma_f32_16x16x32_bf16 v[20:23], v[174:177], v[140:143], v[20:23]
	v_cvt_pk_bf16_f32 v177, v133, v135
	v_cvt_pk_bf16_f32 v176, v129, v131
	v_cvt_pk_bf16_f32 v175, v125, v127
	v_mfma_f32_16x16x32_bf16 v[84:87], v[182:185], v[140:143], v[84:87]
	v_cvt_pk_bf16_f32 v174, v121, v123
	v_cvt_pk_bf16_f32 v143, v132, v134
	v_cvt_pk_bf16_f32 v142, v128, v130
	v_cvt_pk_bf16_f32 v141, v124, v126
	v_cvt_pk_bf16_f32 v140, v120, v122
	s_waitcnt lgkmcnt(14)
	v_mfma_f32_16x16x32_bf16 v[92:95], v[196:199], v[174:177], v[92:95]
	v_mfma_f32_16x16x32_bf16 v[68:71], v[196:199], v[140:143], v[68:71]
	s_waitcnt lgkmcnt(10)
	v_mfma_f32_16x16x32_bf16 v[76:79], v[204:207], v[174:177], v[76:79]
	v_mfma_f32_16x16x32_bf16 v[56:59], v[204:207], v[140:143], v[56:59]
	s_waitcnt lgkmcnt(8)
	v_mfma_f32_16x16x32_bf16 v[72:75], v[208:211], v[174:177], v[72:75]
	v_mfma_f32_16x16x32_bf16 v[24:27], v[208:211], v[140:143], v[24:27]
	s_waitcnt lgkmcnt(6)
	v_mfma_f32_16x16x32_bf16 v[60:63], v[212:215], v[174:177], v[60:63]
	v_mfma_f32_16x16x32_bf16 v[64:67], v[212:215], v[140:143], v[64:67]
	s_waitcnt lgkmcnt(4)
	v_mfma_f32_16x16x32_bf16 v[28:31], v[216:219], v[174:177], v[28:31]
	v_mfma_f32_16x16x32_bf16 v[44:47], v[216:219], v[140:143], v[44:47]
	s_waitcnt lgkmcnt(2)
	v_mfma_f32_16x16x32_bf16 v[20:23], v[220:223], v[174:177], v[20:23]
	v_mfma_f32_16x16x32_bf16 v[32:35], v[220:223], v[140:143], v[32:35]
	v_mfma_f32_16x16x32_bf16 v[96:99], v[200:203], v[174:177], v[96:99]
	v_mfma_f32_16x16x32_bf16 v[80:83], v[200:203], v[140:143], v[80:83]
	s_waitcnt lgkmcnt(0)
	v_mfma_f32_16x16x32_bf16 v[84:87], v[226:229], v[174:177], v[84:87]
	v_mfma_f32_16x16x32_bf16 v[88:91], v[226:229], v[140:143], v[88:91]
	s_and_saveexec_b64 s[10:11], s[6:7]
	s_cbranch_execz .LBB0_717
	s_cmp_eq_u32 s13, 1
	s_cselect_b32 s6, 0x8c00, 0
	s_add_i32 s6, s6, 16
	v_add3_u32 v139, s6, v155, v102
	s_waitcnt vmcnt(0)
	ds_write_b128 v139, v[4:7]
	ds_write_b128 v139, v[8:11] offset:8704
	v_add3_u32 v139, s6, v156, v104
	ds_write_b128 v139, v[12:15] offset:17408
	ds_write_b128 v139, v[16:19] offset:26624
	s_branch .LBB0_717
